# acc zero-init with 64-bit moves; pool mixer initial window loads issued four at a time
# baseline (speedup 1.0000x reference)
; __device__ __forceinline__ void poolmix_phase(const bf16_t* __restrict__ XB, const pg8::ssq_t* __restrict__ ssq, const float* __restrict__ g, bf16_t* __restrict__ MX, int row_lo, int nrows, int gtid, int nthr, LAS unsigned char* lds, int tid) {
;     ...
;         for (int tt = t0 - hw; tt < t0 + w - hw; ++tt) PM_V(tt, 1.f);
.LBB0_161:
	v_add_u32_e32 v25, 4, v25
	v_cmp_ge_i32_e32 vcc, v25, v11
	v_add_u32_e32 v24, 16, v24
	s_or_b64 s[12:13], vcc, s[12:13]
	v_add_u32_e32 v176, 0x4000, v176
	s_andn2_b64 exec, exec, s[12:13]
	s_cbranch_execz .LBB0_164
.LBB0_162:
	v_cmp_gt_u32_e32 vcc, s57, v25
	v_cmp_lt_i32_e64 s[14:15], v25, v11
	s_and_b64 vcc, vcc, s[14:15]
	s_and_saveexec_b64 s[14:15], vcc
	v_lshl_add_u64 v[52:53], v[12:13], 0, v[176:177]
	global_load_dwordx4 v[56:59], v[52:53], off
	s_or_b64 exec, exec, s[14:15]
	v_add_u32_e32 v54, 1, v25
	v_cmp_gt_u32_e32 vcc, s57, v54
	v_cmp_lt_i32_e64 s[14:15], v54, v11
	s_and_b64 vcc, vcc, s[14:15]
	s_and_saveexec_b64 s[14:15], vcc
	v_add_u32_e32 v54, 0x1000, v176
	v_mov_b32_e32 v55, 0
	v_lshl_add_u64 v[52:53], v[12:13], 0, v[54:55]
	global_load_dwordx4 v[60:63], v[52:53], off
	s_or_b64 exec, exec, s[14:15]
	v_add_u32_e32 v54, 2, v25
	v_cmp_gt_u32_e32 vcc, s57, v54
	v_cmp_lt_i32_e64 s[14:15], v54, v11
	s_and_b64 vcc, vcc, s[14:15]
	s_and_saveexec_b64 s[14:15], vcc
	v_add_u32_e32 v54, 0x2000, v176
	v_mov_b32_e32 v55, 0
	v_lshl_add_u64 v[52:53], v[12:13], 0, v[54:55]
	global_load_dwordx4 v[64:67], v[52:53], off
	s_or_b64 exec, exec, s[14:15]
	v_add_u32_e32 v54, 3, v25
	v_cmp_gt_u32_e32 vcc, s57, v54
	v_cmp_lt_i32_e64 s[14:15], v54, v11
	s_and_b64 vcc, vcc, s[14:15]
	s_and_saveexec_b64 s[14:15], vcc
	v_add_u32_e32 v54, 0x3000, v176
	v_mov_b32_e32 v55, 0
	v_lshl_add_u64 v[52:53], v[12:13], 0, v[54:55]
	global_load_dwordx4 v[68:71], v[52:53], off
	s_or_b64 exec, exec, s[14:15]
	v_cmp_gt_u32_e32 vcc, s57, v25
	v_cmp_lt_i32_e64 s[14:15], v25, v11
	s_and_b64 vcc, vcc, s[14:15]
	s_and_saveexec_b64 s[14:15], vcc
	s_cbranch_execz .Lpoolinit_skip0
	ds_read_b32 v32, v24
	s_waitcnt vmcnt(3)
	v_lshlrev_b32_e32 v40, 16, v56
	v_and_b32_e32 v41, 0xffff0000, v56
	v_lshlrev_b32_e32 v36, 16, v57
	v_and_b32_e32 v37, 0xffff0000, v57
	s_waitcnt lgkmcnt(0)
	v_pk_fma_f32 v[18:19], v[32:33], v[36:37], v[18:19] op_sel_hi:[0,1,1]
	v_lshlrev_b32_e32 v36, 16, v58
	v_and_b32_e32 v37, 0xffff0000, v58
	v_pk_fma_f32 v[20:21], v[32:33], v[36:37], v[20:21] op_sel_hi:[0,1,1]
	v_lshlrev_b32_e32 v36, 16, v59
	v_and_b32_e32 v37, 0xffff0000, v59
	v_pk_fma_f32 v[16:17], v[32:33], v[40:41], v[16:17] op_sel_hi:[0,1,1]
	v_pk_fma_f32 v[22:23], v[32:33], v[36:37], v[22:23] op_sel_hi:[0,1,1]
.Lpoolinit_skip0:
	s_or_b64 exec, exec, s[14:15]
	v_add_u32_e32 v54, 1, v25
	v_cmp_gt_u32_e32 vcc, s57, v54
	v_cmp_lt_i32_e64 s[14:15], v54, v11
	s_and_b64 vcc, vcc, s[14:15]
	s_and_saveexec_b64 s[14:15], vcc
	s_cbranch_execz .Lpoolinit_skip1
	ds_read_b32 v32, v24 offset:4
	s_waitcnt vmcnt(2)
	v_lshlrev_b32_e32 v40, 16, v60
	v_and_b32_e32 v41, 0xffff0000, v60
	v_lshlrev_b32_e32 v36, 16, v61
	v_and_b32_e32 v37, 0xffff0000, v61
	s_waitcnt lgkmcnt(0)
	v_pk_fma_f32 v[18:19], v[32:33], v[36:37], v[18:19] op_sel_hi:[0,1,1]
	v_lshlrev_b32_e32 v36, 16, v62
	v_and_b32_e32 v37, 0xffff0000, v62
	v_pk_fma_f32 v[20:21], v[32:33], v[36:37], v[20:21] op_sel_hi:[0,1,1]
	v_lshlrev_b32_e32 v36, 16, v63
	v_and_b32_e32 v37, 0xffff0000, v63
	v_pk_fma_f32 v[16:17], v[32:33], v[40:41], v[16:17] op_sel_hi:[0,1,1]
	v_pk_fma_f32 v[22:23], v[32:33], v[36:37], v[22:23] op_sel_hi:[0,1,1]
.Lpoolinit_skip1:
	s_or_b64 exec, exec, s[14:15]
	v_add_u32_e32 v54, 2, v25
	v_cmp_gt_u32_e32 vcc, s57, v54
	v_cmp_lt_i32_e64 s[14:15], v54, v11
	s_and_b64 vcc, vcc, s[14:15]
	s_and_saveexec_b64 s[14:15], vcc
	s_cbranch_execz .Lpoolinit_skip2
	ds_read_b32 v32, v24 offset:8
	s_waitcnt vmcnt(1)
	v_lshlrev_b32_e32 v40, 16, v64
	v_and_b32_e32 v41, 0xffff0000, v64
	v_lshlrev_b32_e32 v36, 16, v65
	v_and_b32_e32 v37, 0xffff0000, v65
	s_waitcnt lgkmcnt(0)
	v_pk_fma_f32 v[18:19], v[32:33], v[36:37], v[18:19] op_sel_hi:[0,1,1]
	v_lshlrev_b32_e32 v36, 16, v66
	v_and_b32_e32 v37, 0xffff0000, v66
	v_pk_fma_f32 v[20:21], v[32:33], v[36:37], v[20:21] op_sel_hi:[0,1,1]
	v_lshlrev_b32_e32 v36, 16, v67
	v_and_b32_e32 v37, 0xffff0000, v67
	v_pk_fma_f32 v[16:17], v[32:33], v[40:41], v[16:17] op_sel_hi:[0,1,1]
	v_pk_fma_f32 v[22:23], v[32:33], v[36:37], v[22:23] op_sel_hi:[0,1,1]
.Lpoolinit_skip2:
	s_or_b64 exec, exec, s[14:15]
	v_add_u32_e32 v54, 3, v25
	v_cmp_gt_u32_e32 vcc, s57, v54
	v_cmp_lt_i32_e64 s[14:15], v54, v11
	s_and_b64 vcc, vcc, s[14:15]
	s_and_saveexec_b64 s[14:15], vcc
	s_cbranch_execz .Lpoolinit_skip3
	ds_read_b32 v32, v24 offset:12
	s_waitcnt vmcnt(0)
	v_lshlrev_b32_e32 v40, 16, v68
	v_and_b32_e32 v41, 0xffff0000, v68
	v_lshlrev_b32_e32 v36, 16, v69
	v_and_b32_e32 v37, 0xffff0000, v69
	s_waitcnt lgkmcnt(0)
	v_pk_fma_f32 v[18:19], v[32:33], v[36:37], v[18:19] op_sel_hi:[0,1,1]
	v_lshlrev_b32_e32 v36, 16, v70
	v_and_b32_e32 v37, 0xffff0000, v70
	v_pk_fma_f32 v[20:21], v[32:33], v[36:37], v[20:21] op_sel_hi:[0,1,1]
	v_lshlrev_b32_e32 v36, 16, v71
	v_and_b32_e32 v37, 0xffff0000, v71
	v_pk_fma_f32 v[16:17], v[32:33], v[40:41], v[16:17] op_sel_hi:[0,1,1]
	v_pk_fma_f32 v[22:23], v[32:33], v[36:37], v[22:23] op_sel_hi:[0,1,1]
.Lpoolinit_skip3:
	s_or_b64 exec, exec, s[14:15]
	s_branch .LBB0_161

; template <bool F16, class Sched, class Epi>
; __device__ __forceinline__ void gemm_phase(LAS unsigned char* lds, const Gemm g, const Sched& S, const Epi& E, int wave_s) {
;     ...
;         const bool has_next = S.next(ui + 1, nxt);
;         const char* nA = has_next ? (const char*)g.A + PG8_AOFF(nxt) : cA + (size_t)(nt - 2) * kstep; const char* nB = has_next ? (const char*)g.Bt + (size_t)nxt.pn * tstepB : cB + (size_t)(nt - 2) * kstep;
;     ...
; #pragma unroll
;         for (int a = 0; a < 2; ++a)
; #pragma unroll
;             for (int b = 0; b < 2; ++b)
; #pragma unroll
;                 for (int m = 0; m < 4; ++m)
; #pragma unroll
;                     for (int n = 0; n < 2; ++n) acc[a][b][m][n] = (f32x4){0.f, 0.f, 0.f, 0.f};
;         cur = nxt; cA = nA; cB = nB; ++ui;
.LBB0_233:
	s_and_b64 s[0:1], s[14:15], exec
	s_cselect_b32 s0, s48, s30
	s_ashr_i32 s1, s0, 31
	s_lshl_b64 s[0:1], s[0:1], 18
	s_add_u32 s24, s37, s0
	s_addc_u32 s25, s38, s1
	s_add_u32 s30, s28, 0x300
	s_addc_u32 s31, s29, 0
	s_and_b64 s[0:1], s[14:15], exec
	s_cselect_b32 s0, s25, s31
	s_cselect_b32 s1, s24, s30
	s_add_u32 s26, s26, 0x80080
	s_addc_u32 s27, s27, 0
	s_add_u32 s53, s28, 0x100
	v_mov_b64_e32 v[0:1], 0
	s_addc_u32 s58, s29, 0
	s_mov_b32 s59, -2
	v_mov_b64_e32 v[2:3], 0
	v_mov_b64_e32 v[4:5], 0
	v_mov_b64_e32 v[6:7], 0
	v_mov_b64_e32 v[8:9], 0
	v_mov_b64_e32 v[10:11], 0
	s_waitcnt lgkmcnt(0)
	v_mov_b64_e32 v[16:17], 0
	v_mov_b64_e32 v[18:19], 0
	v_mov_b64_e32 v[24:25], 0
	v_mov_b64_e32 v[26:27], 0
	v_mov_b64_e32 v[32:33], 0
	v_mov_b64_e32 v[34:35], 0
	v_mov_b64_e32 v[40:41], 0
	v_mov_b64_e32 v[42:43], 0
	v_mov_b64_e32 v[48:49], 0
	v_mov_b64_e32 v[50:51], 0
	v_mov_b64_e32 v[12:13], 0
	v_mov_b64_e32 v[14:15], 0
	v_mov_b64_e32 v[20:21], 0
	v_mov_b64_e32 v[22:23], 0
	v_mov_b64_e32 v[28:29], 0
	v_mov_b64_e32 v[30:31], 0
	v_mov_b64_e32 v[36:37], 0
	v_mov_b64_e32 v[38:39], 0
	v_mov_b64_e32 v[44:45], 0
	v_mov_b64_e32 v[46:47], 0
	v_mov_b64_e32 v[52:53], 0
	v_mov_b64_e32 v[54:55], 0
	v_mov_b64_e32 v[56:57], 0
	v_mov_b64_e32 v[58:59], 0
	v_mov_b64_e32 v[60:61], 0
	v_mov_b64_e32 v[62:63], 0
	v_mov_b64_e32 v[64:65], 0
	v_mov_b64_e32 v[66:67], 0
	v_mov_b64_e32 v[68:69], 0
	v_mov_b64_e32 v[70:71], 0
	v_mov_b64_e32 v[72:73], 0
	v_mov_b64_e32 v[74:75], 0
	v_mov_b64_e32 v[80:81], 0
	v_mov_b64_e32 v[82:83], 0
	v_mov_b64_e32 v[88:89], 0
	v_mov_b64_e32 v[90:91], 0
	v_mov_b64_e32 v[100:101], 0
	v_mov_b64_e32 v[102:103], 0
	v_mov_b64_e32 v[112:113], 0
	v_mov_b64_e32 v[114:115], 0
	v_mov_b64_e32 v[116:117], 0
	v_mov_b64_e32 v[118:119], 0
	v_mov_b64_e32 v[76:77], 0
	v_mov_b64_e32 v[78:79], 0
	v_mov_b64_e32 v[84:85], 0
	v_mov_b64_e32 v[86:87], 0
	v_mov_b64_e32 v[92:93], 0
	v_mov_b64_e32 v[94:95], 0
	v_mov_b64_e32 v[96:97], 0
	v_mov_b64_e32 v[98:99], 0
	v_mov_b64_e32 v[104:105], 0
	v_mov_b64_e32 v[106:107], 0
	v_mov_b64_e32 v[108:109], 0
	v_mov_b64_e32 v[110:111], 0
	v_mov_b64_e32 v[120:121], 0
	v_mov_b64_e32 v[122:123], 0
	v_mov_b64_e32 v[124:125], 0
	v_mov_b64_e32 v[126:127], 0

; template <bool F16, class Sched, class Epi>
; __device__ __forceinline__ void gemm_phase(LAS unsigned char* lds, const Gemm g, const Sched& S, const Epi& E, int wave_s) {
;     ...
;         const bool has_next = S.next(ui + 1, nxt);
;         const char* nA = has_next ? (const char*)g.A + PG8_AOFF(nxt) : cA + (size_t)(nt - 2) * kstep; const char* nB = has_next ? (const char*)g.Bt + (size_t)nxt.pn * tstepB : cB + (size_t)(nt - 2) * kstep;
;     ...
; #pragma unroll
;         for (int a = 0; a < 2; ++a)
; #pragma unroll
;             for (int b = 0; b < 2; ++b)
; #pragma unroll
;                 for (int m = 0; m < 4; ++m)
; #pragma unroll
;                     for (int n = 0; n < 2; ++n) acc[a][b][m][n] = (f32x4){0.f, 0.f, 0.f, 0.f};
;         cur = nxt; cA = nA; cB = nB; ++ui;
.LBB0_303:
	s_add_i32 s61, s61, 1
	s_mov_b64 s[2:3], s[8:9]
	s_mul_i32 s8, s61, s33
	s_add_i32 s8, s8, s21
	s_cmp_lt_i32 s8, 64
	s_cselect_b64 s[36:37], -1, 0
	s_and_b32 s9, s8, 3
	s_mov_b64 s[4:5], s[10:11]
	s_mov_b32 s11, s47
	s_mov_b32 s10, s48
	s_mov_b32 s0, s47
	s_mov_b32 s1, s48
	s_or_b32 s47, s9, s41
	s_ashr_i32 s48, s8, 2
	s_and_b64 s[8:9], s[36:37], exec
	s_cselect_b32 s8, s47, s11
	s_cselect_b32 s10, s48, s10
	s_ashr_i32 s9, s8, 31
	s_lshl_b64 s[8:9], s[8:9], 20
	s_add_u32 s8, s42, s8
	s_addc_u32 s9, s43, s9
	s_add_u32 s11, s2, 0xf00
	s_addc_u32 s62, s3, 0
	s_and_b64 s[38:39], s[36:37], exec
	s_cselect_b32 s62, s9, s62
	s_cselect_b32 s63, s8, s11
	s_ashr_i32 s11, s10, 31
	s_lshl_b64 s[10:11], s[10:11], 20
	s_add_u32 s10, s44, s10
	s_addc_u32 s11, s45, s11
	s_add_u32 s65, s4, 0xf00
	s_addc_u32 s64, s5, 0
	s_and_b64 s[38:39], s[36:37], exec
	s_cselect_b32 s64, s11, s64
	s_cselect_b32 s65, s10, s65
	s_add_u32 s2, s2, 0x80080
	s_addc_u32 s3, s3, 0
	s_add_u32 s68, s4, 0x100
	v_mov_b64_e32 v[0:1], 0
	s_addc_u32 s69, s5, 0
	s_mov_b32 s70, -2
	v_mov_b64_e32 v[2:3], 0
	v_mov_b64_e32 v[4:5], 0
	v_mov_b64_e32 v[6:7], 0
	v_mov_b64_e32 v[16:17], 0
	v_mov_b64_e32 v[18:19], 0
	v_mov_b64_e32 v[20:21], 0
	v_mov_b64_e32 v[22:23], 0
	v_mov_b64_e32 v[32:33], 0
	v_mov_b64_e32 v[34:35], 0
	v_mov_b64_e32 v[36:37], 0
	v_mov_b64_e32 v[38:39], 0
	v_mov_b64_e32 v[48:49], 0
	v_mov_b64_e32 v[50:51], 0
	v_mov_b64_e32 v[52:53], 0
	v_mov_b64_e32 v[54:55], 0
	v_mov_b64_e32 v[8:9], 0
	v_mov_b64_e32 v[10:11], 0
	v_mov_b64_e32 v[12:13], 0
	v_mov_b64_e32 v[14:15], 0
	v_mov_b64_e32 v[24:25], 0
	v_mov_b64_e32 v[26:27], 0
	v_mov_b64_e32 v[28:29], 0
	v_mov_b64_e32 v[30:31], 0
	v_mov_b64_e32 v[40:41], 0
	v_mov_b64_e32 v[42:43], 0
	v_mov_b64_e32 v[44:45], 0
	v_mov_b64_e32 v[46:47], 0
	v_mov_b64_e32 v[56:57], 0
	v_mov_b64_e32 v[58:59], 0
	v_mov_b64_e32 v[60:61], 0
	v_mov_b64_e32 v[62:63], 0
	v_mov_b64_e32 v[64:65], 0
	v_mov_b64_e32 v[66:67], 0
	v_mov_b64_e32 v[68:69], 0
	v_mov_b64_e32 v[70:71], 0
	v_mov_b64_e32 v[80:81], 0
	v_mov_b64_e32 v[82:83], 0
	v_mov_b64_e32 v[84:85], 0
	v_mov_b64_e32 v[86:87], 0
	v_mov_b64_e32 v[96:97], 0
	v_mov_b64_e32 v[98:99], 0
	v_mov_b64_e32 v[100:101], 0
	v_mov_b64_e32 v[102:103], 0
	v_mov_b64_e32 v[112:113], 0
	v_mov_b64_e32 v[114:115], 0
	v_mov_b64_e32 v[116:117], 0
	v_mov_b64_e32 v[118:119], 0
	v_mov_b64_e32 v[72:73], 0
	v_mov_b64_e32 v[74:75], 0
	v_mov_b64_e32 v[76:77], 0
	v_mov_b64_e32 v[78:79], 0
	v_mov_b64_e32 v[88:89], 0
	v_mov_b64_e32 v[90:91], 0
	v_mov_b64_e32 v[92:93], 0
	v_mov_b64_e32 v[94:95], 0
	v_mov_b64_e32 v[104:105], 0
	v_mov_b64_e32 v[106:107], 0
	v_mov_b64_e32 v[108:109], 0
	v_mov_b64_e32 v[110:111], 0
	v_mov_b64_e32 v[120:121], 0
	v_mov_b64_e32 v[122:123], 0
	v_mov_b64_e32 v[124:125], 0
	v_mov_b64_e32 v[126:127], 0

; template <bool F16, class Sched, class Epi>
; __device__ __forceinline__ void gemm_phase(LAS unsigned char* lds, const Gemm g, const Sched& S, const Epi& E, int wave_s) {
;     ...
;         const bool has_next = S.next(ui + 1, nxt);
;         const char* nA = has_next ? (const char*)g.A + PG8_AOFF(nxt) : cA + (size_t)(nt - 2) * kstep; const char* nB = has_next ? (const char*)g.Bt + (size_t)nxt.pn * tstepB : cB + (size_t)(nt - 2) * kstep;
;     ...
; #pragma unroll
;         for (int a = 0; a < 2; ++a)
; #pragma unroll
;             for (int b = 0; b < 2; ++b)
; #pragma unroll
;                 for (int m = 0; m < 4; ++m)
; #pragma unroll
;                     for (int n = 0; n < 2; ++n) acc[a][b][m][n] = (f32x4){0.f, 0.f, 0.f, 0.f};
;         cur = nxt; cA = nA; cB = nB; ++ui;
.LBB0_357:
	s_add_i32 s53, s53, 1
	s_mov_b64 s[30:31], s[4:5]
	s_mul_i32 s4, s53, s33
	s_add_i32 s4, s4, s21
	s_cmp_lt_i32 s4, 32
	s_mov_b64 s[2:3], s[6:7]
	s_mov_b32 s6, s43
	s_mov_b32 s0, s43
	s_cselect_b64 s[28:29], -1, 0
	s_and_b32 s43, s4, 7
	s_ashr_i32 s4, s4, 3
	s_mov_b32 s7, s45
	s_mov_b32 s1, s45
	s_add_i32 s45, s4, s36
	s_and_b64 s[4:5], s[28:29], exec
	s_cselect_b32 s6, s43, s6
	s_cselect_b32 s4, s45, s7
	s_ashr_i32 s7, s6, 31
	s_lshl_b64 s[6:7], s[6:7], 20
	s_add_u32 s6, s37, s6
	s_addc_u32 s7, s38, s7
	s_add_u32 s5, s2, 0xf00
	s_addc_u32 s58, s3, 0
	s_and_b64 s[34:35], s[28:29], exec
	s_cselect_b32 s58, s7, s58
	s_cselect_b32 s59, s6, s5
	s_ashr_i32 s5, s4, 31
	s_lshl_b64 s[4:5], s[4:5], 20
	s_add_u32 s4, s39, s4
	s_addc_u32 s5, s41, s5
	s_add_u32 s61, s30, 0xf00
	s_addc_u32 s60, s31, 0
	s_and_b64 s[34:35], s[28:29], exec
	s_cselect_b32 s60, s5, s60
	s_cselect_b32 s61, s4, s61
	s_add_u32 s2, s2, 0x80080
	s_addc_u32 s3, s3, 0
	s_add_u32 s62, s30, 0x100
	v_mov_b64_e32 v[0:1], 0
	s_addc_u32 s63, s31, 0
	s_mov_b32 s64, -2
	v_mov_b64_e32 v[2:3], 0
	v_mov_b64_e32 v[4:5], 0
	v_mov_b64_e32 v[6:7], 0
	v_mov_b64_e32 v[12:13], 0
	v_mov_b64_e32 v[14:15], 0
	v_mov_b64_e32 v[20:21], 0
	v_mov_b64_e32 v[22:23], 0
	v_mov_b64_e32 v[28:29], 0
	v_mov_b64_e32 v[30:31], 0
	v_mov_b64_e32 v[36:37], 0
	v_mov_b64_e32 v[38:39], 0
	v_mov_b64_e32 v[44:45], 0
	v_mov_b64_e32 v[46:47], 0
	v_mov_b64_e32 v[52:53], 0
	v_mov_b64_e32 v[54:55], 0
	v_mov_b64_e32 v[8:9], 0
	v_mov_b64_e32 v[10:11], 0
	v_mov_b64_e32 v[16:17], 0
	v_mov_b64_e32 v[18:19], 0
	v_mov_b64_e32 v[24:25], 0
	v_mov_b64_e32 v[26:27], 0
	v_mov_b64_e32 v[32:33], 0
	v_mov_b64_e32 v[34:35], 0
	v_mov_b64_e32 v[40:41], 0
	v_mov_b64_e32 v[42:43], 0
	v_mov_b64_e32 v[48:49], 0
	v_mov_b64_e32 v[50:51], 0
	v_mov_b64_e32 v[56:57], 0
	v_mov_b64_e32 v[58:59], 0
	v_mov_b64_e32 v[60:61], 0
	v_mov_b64_e32 v[62:63], 0
	v_mov_b64_e32 v[64:65], 0
	v_mov_b64_e32 v[66:67], 0
	v_mov_b64_e32 v[68:69], 0
	v_mov_b64_e32 v[70:71], 0
	v_mov_b64_e32 v[80:81], 0
	v_mov_b64_e32 v[82:83], 0
	v_mov_b64_e32 v[84:85], 0
	v_mov_b64_e32 v[86:87], 0
	v_mov_b64_e32 v[96:97], 0
	v_mov_b64_e32 v[98:99], 0
	v_mov_b64_e32 v[100:101], 0
	v_mov_b64_e32 v[102:103], 0
	v_mov_b64_e32 v[112:113], 0
	v_mov_b64_e32 v[114:115], 0
	v_mov_b64_e32 v[116:117], 0
	v_mov_b64_e32 v[118:119], 0
	v_mov_b64_e32 v[72:73], 0
	v_mov_b64_e32 v[74:75], 0
	v_mov_b64_e32 v[76:77], 0
	v_mov_b64_e32 v[78:79], 0
	v_mov_b64_e32 v[88:89], 0
	v_mov_b64_e32 v[90:91], 0
	v_mov_b64_e32 v[92:93], 0
	v_mov_b64_e32 v[94:95], 0
	v_mov_b64_e32 v[104:105], 0
	v_mov_b64_e32 v[106:107], 0
	v_mov_b64_e32 v[108:109], 0
	v_mov_b64_e32 v[110:111], 0
	v_mov_b64_e32 v[120:121], 0
	v_mov_b64_e32 v[122:123], 0
	v_mov_b64_e32 v[124:125], 0
	v_mov_b64_e32 v[126:127], 0

; template <bool F16, class Sched, class Epi>
; __device__ __forceinline__ void gemm_phase(LAS unsigned char* lds, const Gemm g, const Sched& S, const Epi& E, int wave_s) {
;     ...
;         const bool has_next = S.next(ui + 1, nxt);
;         const char* nA = has_next ? (const char*)g.A + PG8_AOFF(nxt) : cA + (size_t)(nt - 2) * kstep; const char* nB = has_next ? (const char*)g.Bt + (size_t)nxt.pn * tstepB : cB + (size_t)(nt - 2) * kstep;
;     ...
; #pragma unroll
;         for (int a = 0; a < 2; ++a)
; #pragma unroll
;             for (int b = 0; b < 2; ++b)
; #pragma unroll
;                 for (int m = 0; m < 4; ++m)
; #pragma unroll
;                     for (int n = 0; n < 2; ++n) acc[a][b][m][n] = (f32x4){0.f, 0.f, 0.f, 0.f};
;         cur = nxt; cA = nA; cB = nB; ++ui;
.LBB0_597:
	s_add_i32 s48, s48, 1
	s_mov_b64 s[26:27], s[4:5]
	s_mul_i32 s4, s48, s33
	s_add_i32 s4, s4, s21
	s_cmp_lt_i32 s4, 32
	s_cselect_b64 s[24:25], -1, 0
	s_and_b32 s5, s4, 3
	s_mov_b64 s[28:29], s[6:7]
	s_mov_b32 s7, s41
	s_mov_b32 s6, s42
	s_mov_b32 s1, s41
	s_mov_b32 s0, s42
	s_or_b32 s41, s5, s34
	s_ashr_i32 s42, s4, 2
	s_and_b64 s[4:5], s[24:25], exec
	s_cselect_b32 s4, s41, s7
	s_cselect_b32 s6, s42, s6
	s_ashr_i32 s5, s4, 31
	s_lshl_b64 s[4:5], s[4:5], 20
	s_add_u32 s4, s35, s4
	s_addc_u32 s5, s36, s5
	s_add_u32 s7, s26, 0xf00
	s_addc_u32 s49, s27, 0
	s_and_b64 s[30:31], s[24:25], exec
	s_cselect_b32 s49, s5, s49
	s_cselect_b32 s50, s4, s7
	s_ashr_i32 s7, s6, 31
	s_lshl_b64 s[6:7], s[6:7], 20
	s_add_u32 s6, s37, s6
	s_addc_u32 s7, s38, s7
	s_add_u32 s53, s28, 0xf00
	s_addc_u32 s52, s29, 0
	s_and_b64 s[30:31], s[24:25], exec
	s_cselect_b32 s52, s7, s52
	s_cselect_b32 s53, s6, s53
	s_add_u32 s26, s26, 0x80080
	s_addc_u32 s27, s27, 0
	s_add_u32 s58, s28, 0x100
	v_mov_b64_e32 v[0:1], 0
	s_addc_u32 s59, s29, 0
	s_mov_b32 s60, -2
	v_mov_b64_e32 v[2:3], 0
	v_mov_b64_e32 v[4:5], 0
	v_mov_b64_e32 v[6:7], 0
	v_mov_b64_e32 v[8:9], 0
	v_mov_b64_e32 v[10:11], 0
	s_waitcnt lgkmcnt(0)
	v_mov_b64_e32 v[16:17], 0
	v_mov_b64_e32 v[18:19], 0
	v_mov_b64_e32 v[24:25], 0
	v_mov_b64_e32 v[26:27], 0
	v_mov_b64_e32 v[32:33], 0
	v_mov_b64_e32 v[34:35], 0
	v_mov_b64_e32 v[40:41], 0
	v_mov_b64_e32 v[42:43], 0
	v_mov_b64_e32 v[48:49], 0
	v_mov_b64_e32 v[50:51], 0
	v_mov_b64_e32 v[12:13], 0
	v_mov_b64_e32 v[14:15], 0
	v_mov_b64_e32 v[20:21], 0
	v_mov_b64_e32 v[22:23], 0
	v_mov_b64_e32 v[28:29], 0
	v_mov_b64_e32 v[30:31], 0
	v_mov_b64_e32 v[36:37], 0
	v_mov_b64_e32 v[38:39], 0
	v_mov_b64_e32 v[44:45], 0
	v_mov_b64_e32 v[46:47], 0
	v_mov_b64_e32 v[52:53], 0
	v_mov_b64_e32 v[54:55], 0
	v_mov_b64_e32 v[56:57], 0
	v_mov_b64_e32 v[58:59], 0
	v_mov_b64_e32 v[60:61], 0
	v_mov_b64_e32 v[62:63], 0
	v_mov_b64_e32 v[64:65], 0
	v_mov_b64_e32 v[66:67], 0
	v_mov_b64_e32 v[68:69], 0
	v_mov_b64_e32 v[70:71], 0
	v_mov_b64_e32 v[72:73], 0
	v_mov_b64_e32 v[74:75], 0
	v_mov_b64_e32 v[80:81], 0
	v_mov_b64_e32 v[82:83], 0
	v_mov_b64_e32 v[88:89], 0
	v_mov_b64_e32 v[90:91], 0
	v_mov_b64_e32 v[100:101], 0
	v_mov_b64_e32 v[102:103], 0
	v_mov_b64_e32 v[112:113], 0
	v_mov_b64_e32 v[114:115], 0
	v_mov_b64_e32 v[116:117], 0
	v_mov_b64_e32 v[118:119], 0
	v_mov_b64_e32 v[76:77], 0
	v_mov_b64_e32 v[78:79], 0
	v_mov_b64_e32 v[84:85], 0
	v_mov_b64_e32 v[86:87], 0
	v_mov_b64_e32 v[92:93], 0
	v_mov_b64_e32 v[94:95], 0
	v_mov_b64_e32 v[96:97], 0
	v_mov_b64_e32 v[98:99], 0
	v_mov_b64_e32 v[104:105], 0
	v_mov_b64_e32 v[106:107], 0
	v_mov_b64_e32 v[108:109], 0
	v_mov_b64_e32 v[110:111], 0
	v_mov_b64_e32 v[120:121], 0
	v_mov_b64_e32 v[122:123], 0
	v_mov_b64_e32 v[124:125], 0
	v_mov_b64_e32 v[126:127], 0

; template <bool F16, class Sched, class Epi>
; __device__ __forceinline__ void gemm_phase(LAS unsigned char* lds, const Gemm g, const Sched& S, const Epi& E, int wave_s) {
;     ...
;         const bool has_next = S.next(ui + 1, nxt);
;         const char* nA = has_next ? (const char*)g.A + PG8_AOFF(nxt) : cA + (size_t)(nt - 2) * kstep; const char* nB = has_next ? (const char*)g.Bt + (size_t)nxt.pn * tstepB : cB + (size_t)(nt - 2) * kstep;
;     ...
; #pragma unroll
;         for (int a = 0; a < 2; ++a)
; #pragma unroll
;             for (int b = 0; b < 2; ++b)
; #pragma unroll
;                 for (int m = 0; m < 4; ++m)
; #pragma unroll
;                     for (int n = 0; n < 2; ++n) acc[a][b][m][n] = (f32x4){0.f, 0.f, 0.f, 0.f};
;         cur = nxt; cA = nA; cB = nB; ++ui;
.LBB0_680:
	s_add_i32 s48, s48, 1
	s_mov_b64 s[26:27], s[2:3]
	s_mul_i32 s2, s48, s33
	s_add_i32 s2, s2, s30
	s_cmpk_lt_i32 s2, 0xb0
	s_cselect_b64 s[14:15], -1, 0
	s_and_b32 s3, s2, 3
	s_mov_b64 s[24:25], s[6:7]
	s_mov_b32 s6, s41
	s_mov_b32 s7, s42
	s_mov_b32 s1, s41
	s_mov_b32 s0, s42
	s_or_b32 s41, s3, s31
	s_ashr_i32 s42, s2, 2
	s_and_b64 s[2:3], s[14:15], exec
	s_cselect_b32 s6, s41, s6
	s_cselect_b32 s2, s42, s7
	s_ashr_i32 s7, s6, 31
	s_lshl_b64 s[6:7], s[6:7], 20
	s_add_u32 s6, s34, s6
	s_addc_u32 s7, s35, s7
	s_add_u32 s3, s24, 0xf00
	s_addc_u32 s49, s25, 0
	s_and_b64 s[28:29], s[14:15], exec
	s_cselect_b32 s49, s7, s49
	s_cselect_b32 s50, s6, s3
	s_ashr_i32 s3, s2, 31
	s_lshl_b64 s[2:3], s[2:3], 20
	s_add_u32 s2, s36, s2
	s_addc_u32 s3, s37, s3
	s_add_u32 s53, s26, 0xf00
	s_addc_u32 s52, s27, 0
	s_and_b64 s[28:29], s[14:15], exec
	s_cselect_b32 s52, s3, s52
	s_cselect_b32 s53, s2, s53
	s_add_u32 s24, s24, 0x80080
	s_addc_u32 s25, s25, 0
	s_add_u32 s58, s26, 0x100
	v_mov_b64_e32 v[0:1], 0
	s_addc_u32 s59, s27, 0
	s_mov_b32 s60, -2
	v_mov_b64_e32 v[2:3], 0
	v_mov_b64_e32 v[8:9], 0
	v_mov_b64_e32 v[10:11], 0
	v_mov_b64_e32 v[16:17], 0
	v_mov_b64_e32 v[18:19], 0
	v_mov_b64_e32 v[24:25], 0
	v_mov_b64_e32 v[26:27], 0
	v_mov_b64_e32 v[32:33], 0
	v_mov_b64_e32 v[34:35], 0
	v_mov_b64_e32 v[40:41], 0
	v_mov_b64_e32 v[42:43], 0
	v_mov_b64_e32 v[48:49], 0
	v_mov_b64_e32 v[50:51], 0
	v_mov_b64_e32 v[56:57], 0
	v_mov_b64_e32 v[58:59], 0
	v_mov_b64_e32 v[4:5], 0
	v_mov_b64_e32 v[6:7], 0
	v_mov_b64_e32 v[12:13], 0
	v_mov_b64_e32 v[14:15], 0
	v_mov_b64_e32 v[20:21], 0
	v_mov_b64_e32 v[22:23], 0
	v_mov_b64_e32 v[28:29], 0
	v_mov_b64_e32 v[30:31], 0
	v_mov_b64_e32 v[36:37], 0
	v_mov_b64_e32 v[38:39], 0
	v_mov_b64_e32 v[44:45], 0
	v_mov_b64_e32 v[46:47], 0
	v_mov_b64_e32 v[52:53], 0
	v_mov_b64_e32 v[54:55], 0
	v_mov_b64_e32 v[60:61], 0
	v_mov_b64_e32 v[62:63], 0
	v_mov_b64_e32 v[64:65], 0
	v_mov_b64_e32 v[66:67], 0
	v_mov_b64_e32 v[72:73], 0
	v_mov_b64_e32 v[74:75], 0
	v_mov_b64_e32 v[80:81], 0
	v_mov_b64_e32 v[82:83], 0
	v_mov_b64_e32 v[88:89], 0
	v_mov_b64_e32 v[90:91], 0
	v_mov_b64_e32 v[96:97], 0
	v_mov_b64_e32 v[98:99], 0
	v_mov_b64_e32 v[104:105], 0
	v_mov_b64_e32 v[106:107], 0
	v_mov_b64_e32 v[112:113], 0
	v_mov_b64_e32 v[114:115], 0
	v_mov_b64_e32 v[120:121], 0
	v_mov_b64_e32 v[122:123], 0
	v_mov_b64_e32 v[68:69], 0
	v_mov_b64_e32 v[70:71], 0
	v_mov_b64_e32 v[76:77], 0
	v_mov_b64_e32 v[78:79], 0
	v_mov_b64_e32 v[84:85], 0
	v_mov_b64_e32 v[86:87], 0
	v_mov_b64_e32 v[92:93], 0
	v_mov_b64_e32 v[94:95], 0
	v_mov_b64_e32 v[100:101], 0
	v_mov_b64_e32 v[102:103], 0
	v_mov_b64_e32 v[108:109], 0
	v_mov_b64_e32 v[110:111], 0
	v_mov_b64_e32 v[116:117], 0
	v_mov_b64_e32 v[118:119], 0
	v_mov_b64_e32 v[124:125], 0
	v_mov_b64_e32 v[126:127], 0

; template <bool F16, class Sched, class Epi>
; __device__ __forceinline__ void gemm_phase(LAS unsigned char* lds, const Gemm g, const Sched& S, const Epi& E, int wave_s) {
;     ...
; #pragma unroll
;         for (int a = 0; a < 2; ++a)
; #pragma unroll
;             for (int b = 0; b < 2; ++b)
; #pragma unroll
;                 for (int m = 0; m < 4; ++m)
; #pragma unroll
;                     for (int n = 0; n < 2; ++n) acc[a][b][m][n] = (f32x4){0.f, 0.f, 0.f, 0.f};
;         cur = nxt; cA = nA; cB = nB; ++ui;
.LBB0_794:
	s_add_u32 s0, s30, 0x100
	v_mov_b64_e32 v[0:1], 0
	s_addc_u32 s1, s31, 0
	s_mov_b32 s63, -2
	v_mov_b64_e32 v[2:3], 0
	v_mov_b64_e32 v[4:5], 0
	v_mov_b64_e32 v[6:7], 0
	v_mov_b64_e32 v[8:9], 0
	v_mov_b64_e32 v[10:11], 0
	s_waitcnt lgkmcnt(0)
	v_mov_b64_e32 v[16:17], 0
	v_mov_b64_e32 v[18:19], 0
	v_mov_b64_e32 v[24:25], 0
	v_mov_b64_e32 v[26:27], 0
	v_mov_b64_e32 v[32:33], 0
	v_mov_b64_e32 v[34:35], 0
	v_mov_b64_e32 v[40:41], 0
	v_mov_b64_e32 v[42:43], 0
	v_mov_b64_e32 v[48:49], 0
	v_mov_b64_e32 v[50:51], 0
	v_mov_b64_e32 v[12:13], 0
	v_mov_b64_e32 v[14:15], 0
	v_mov_b64_e32 v[20:21], 0
	v_mov_b64_e32 v[22:23], 0
	v_mov_b64_e32 v[28:29], 0
	v_mov_b64_e32 v[30:31], 0
	v_mov_b64_e32 v[36:37], 0
	v_mov_b64_e32 v[38:39], 0
	v_mov_b64_e32 v[44:45], 0
	v_mov_b64_e32 v[46:47], 0
	v_mov_b64_e32 v[52:53], 0
	v_mov_b64_e32 v[54:55], 0
	v_mov_b64_e32 v[56:57], 0
	v_mov_b64_e32 v[58:59], 0
	v_mov_b64_e32 v[60:61], 0
	v_mov_b64_e32 v[62:63], 0
	v_mov_b64_e32 v[64:65], 0
	v_mov_b64_e32 v[66:67], 0
	v_mov_b64_e32 v[68:69], 0
	v_mov_b64_e32 v[70:71], 0
	v_mov_b64_e32 v[72:73], 0
	v_mov_b64_e32 v[74:75], 0
	v_mov_b64_e32 v[80:81], 0
	v_mov_b64_e32 v[82:83], 0
	v_mov_b64_e32 v[88:89], 0
	v_mov_b64_e32 v[90:91], 0
	v_mov_b64_e32 v[100:101], 0
	v_mov_b64_e32 v[102:103], 0
	v_mov_b64_e32 v[112:113], 0
	v_mov_b64_e32 v[114:115], 0
	v_mov_b64_e32 v[116:117], 0
	v_mov_b64_e32 v[118:119], 0
	v_mov_b64_e32 v[76:77], 0
	v_mov_b64_e32 v[78:79], 0
	v_mov_b64_e32 v[84:85], 0
	v_mov_b64_e32 v[86:87], 0
	v_mov_b64_e32 v[92:93], 0
	v_mov_b64_e32 v[94:95], 0
	v_mov_b64_e32 v[96:97], 0
	v_mov_b64_e32 v[98:99], 0
	v_mov_b64_e32 v[104:105], 0
	v_mov_b64_e32 v[106:107], 0
	v_mov_b64_e32 v[108:109], 0
	v_mov_b64_e32 v[110:111], 0
	v_mov_b64_e32 v[120:121], 0
	v_mov_b64_e32 v[122:123], 0
	v_mov_b64_e32 v[124:125], 0
	v_mov_b64_e32 v[126:127], 0

; template <bool F16, class Sched, class Epi>
; __device__ __forceinline__ void gemm_phase(LAS unsigned char* lds, const Gemm g, const Sched& S, const Epi& E, int wave_s) {
;     ...
;         const bool has_next = S.next(ui + 1, nxt);
;         const char* nA = has_next ? (const char*)g.A + PG8_AOFF(nxt) : cA + (size_t)(nt - 2) * kstep; const char* nB = has_next ? (const char*)g.Bt + (size_t)nxt.pn * tstepB : cB + (size_t)(nt - 2) * kstep;
;     ...
; #pragma unroll
;         for (int a = 0; a < 2; ++a)
; #pragma unroll
;             for (int b = 0; b < 2; ++b)
; #pragma unroll
;                 for (int m = 0; m < 4; ++m)
; #pragma unroll
;                     for (int n = 0; n < 2; ++n) acc[a][b][m][n] = (f32x4){0.f, 0.f, 0.f, 0.f};
;         cur = nxt; cA = nA; cB = nB; ++ui;
.LBB0_868:
	s_add_i32 s48, s48, 1
	s_mov_b64 s[4:5], s[10:11]
	s_mul_i32 s10, s48, s33
	s_add_i32 s10, s10, s36
	s_cmp_lt_i32 s10, 32
	s_cselect_b64 s[28:29], -1, 0
	s_and_b32 s11, s10, 3
	s_mov_b64 s[30:31], s[12:13]
	s_mov_b32 s13, s42
	s_mov_b32 s12, s43
	s_mov_b32 s1, s42
	s_mov_b32 s0, s43
	s_or_b32 s42, s11, s37
	s_ashr_i32 s43, s10, 2
	s_and_b64 s[10:11], s[28:29], exec
	s_cselect_b32 s10, s42, s13
	s_cselect_b32 s12, s43, s12
	s_ashr_i32 s11, s10, 31
	s_lshl_b64 s[10:11], s[10:11], 20
	s_add_u32 s10, s6, s10
	s_addc_u32 s11, s7, s11
	s_add_u32 s13, s4, 0xf00
	s_addc_u32 s53, s5, 0
	s_and_b64 s[34:35], s[28:29], exec
	s_cselect_b32 s53, s11, s53
	s_cselect_b32 s58, s10, s13
	s_ashr_i32 s13, s12, 31
	s_lshl_b64 s[12:13], s[12:13], 20
	s_add_u32 s12, s38, s12
	s_addc_u32 s13, s39, s13
	s_add_u32 s60, s30, 0xf00
	s_addc_u32 s59, s31, 0
	s_and_b64 s[34:35], s[28:29], exec
	s_cselect_b32 s59, s13, s59
	s_cselect_b32 s60, s12, s60
	s_add_u32 s4, s4, 0x80080
	s_addc_u32 s5, s5, 0
	s_add_u32 s61, s30, 0x100
	v_mov_b64_e32 v[0:1], 0
	s_addc_u32 s62, s31, 0
	s_mov_b32 s63, -2
	v_mov_b64_e32 v[2:3], 0
	v_mov_b64_e32 v[4:5], 0
	v_mov_b64_e32 v[6:7], 0
	s_waitcnt lgkmcnt(0)
	v_mov_b64_e32 v[16:17], 0
	v_mov_b64_e32 v[18:19], 0
	v_mov_b64_e32 v[20:21], 0
	v_mov_b64_e32 v[22:23], 0
	v_mov_b64_e32 v[48:49], 0
	v_mov_b64_e32 v[50:51], 0
	v_mov_b64_e32 v[52:53], 0
	v_mov_b64_e32 v[54:55], 0
	v_mov_b64_e32 v[64:65], 0
	v_mov_b64_e32 v[66:67], 0
	v_mov_b64_e32 v[68:69], 0
	v_mov_b64_e32 v[70:71], 0
	v_mov_b64_e32 v[8:9], 0
	v_mov_b64_e32 v[10:11], 0
	v_mov_b64_e32 v[12:13], 0
	v_mov_b64_e32 v[14:15], 0
	v_mov_b64_e32 v[24:25], 0
	v_mov_b64_e32 v[26:27], 0
	v_mov_b64_e32 v[28:29], 0
	v_mov_b64_e32 v[30:31], 0
	v_mov_b64_e32 v[56:57], 0
	v_mov_b64_e32 v[58:59], 0
	v_mov_b64_e32 v[60:61], 0
	v_mov_b64_e32 v[62:63], 0
	v_mov_b64_e32 v[72:73], 0
	v_mov_b64_e32 v[74:75], 0
	v_mov_b64_e32 v[76:77], 0
	v_mov_b64_e32 v[78:79], 0
	v_mov_b64_e32 v[80:81], 0
	v_mov_b64_e32 v[82:83], 0
	v_mov_b64_e32 v[84:85], 0
	v_mov_b64_e32 v[86:87], 0
	v_mov_b64_e32 v[96:97], 0
	v_mov_b64_e32 v[98:99], 0
	v_mov_b64_e32 v[100:101], 0
	v_mov_b64_e32 v[102:103], 0
	v_mov_b64_e32 v[112:113], 0
	v_mov_b64_e32 v[114:115], 0
	v_mov_b64_e32 v[116:117], 0
	v_mov_b64_e32 v[118:119], 0
	v_mov_b64_e32 v[128:129], 0
	v_mov_b64_e32 v[130:131], 0
	v_mov_b64_e32 v[132:133], 0
	v_mov_b64_e32 v[134:135], 0
	v_mov_b64_e32 v[88:89], 0
	v_mov_b64_e32 v[90:91], 0
	v_mov_b64_e32 v[92:93], 0
	v_mov_b64_e32 v[94:95], 0
	v_mov_b64_e32 v[104:105], 0
	v_mov_b64_e32 v[106:107], 0
	v_mov_b64_e32 v[108:109], 0
	v_mov_b64_e32 v[110:111], 0
	v_mov_b64_e32 v[120:121], 0
	v_mov_b64_e32 v[122:123], 0
	v_mov_b64_e32 v[124:125], 0
	v_mov_b64_e32 v[126:127], 0
	v_mov_b64_e32 v[136:137], 0
	v_mov_b64_e32 v[138:139], 0
	v_mov_b64_e32 v[140:141], 0
	v_mov_b64_e32 v[142:143], 0

; template <bool F16, class Sched, class Epi>
; __device__ __forceinline__ void gemm_phase(LAS unsigned char* lds, const Gemm g, const Sched& S, const Epi& E, int wave_s) {
;     ...
;         const bool has_next = S.next(ui + 1, nxt);
;         const char* nA = has_next ? (const char*)g.A + PG8_AOFF(nxt) : cA + (size_t)(nt - 2) * kstep; const char* nB = has_next ? (const char*)g.Bt + (size_t)nxt.pn * tstepB : cB + (size_t)(nt - 2) * kstep;
;     ...
; #pragma unroll
;         for (int a = 0; a < 2; ++a)
; #pragma unroll
;             for (int b = 0; b < 2; ++b)
; #pragma unroll
;                 for (int m = 0; m < 4; ++m)
; #pragma unroll
;                     for (int n = 0; n < 2; ++n) acc[a][b][m][n] = (f32x4){0.f, 0.f, 0.f, 0.f};
;         cur = nxt; cA = nA; cB = nB; ++ui;
.LBB0_992:
	s_add_i32 s23, s23, 1
	s_mul_i32 s4, s23, s33
	s_add_i32 s4, s4, s41
	s_cmp_lt_i32 s4, 32
	s_cselect_b64 s[62:63], -1, 0
	s_and_b32 s5, s4, 3
	s_mov_b32 s7, s16
	s_mov_b32 s6, s17
	s_mov_b32 s1, s16
	s_mov_b32 s0, s17
	s_or_b32 s16, s5, s12
	s_ashr_i32 s17, s4, 2
	s_and_b64 s[4:5], s[62:63], exec
	s_cselect_b32 s4, s16, s7
	s_cselect_b32 s6, s17, s6
	s_ashr_i32 s5, s4, 31
	s_lshl_b64 s[4:5], s[4:5], 20
	s_mov_b64 s[8:9], s[74:75]
	s_add_u32 s74, s70, s4
	s_addc_u32 s75, s71, s5
	s_add_u32 s7, s8, 0xf00
	s_addc_u32 s38, s9, 0
	s_and_b64 s[4:5], s[62:63], exec
	s_cselect_b32 s4, s75, s38
	s_cselect_b32 s5, s74, s7
	s_ashr_i32 s7, s6, 31
	s_lshl_b64 s[6:7], s[6:7], 20
	s_mov_b64 s[24:25], s[72:73]
	s_add_u32 s72, s13, s6
	s_addc_u32 s73, s14, s7
	s_add_u32 s38, s24, 0xf00
	s_addc_u32 s39, s25, 0
	s_and_b64 s[6:7], s[62:63], exec
	s_cselect_b32 s6, s73, s39
	s_cselect_b32 s7, s72, s38
	s_add_u32 s38, s8, 0x80080
	s_addc_u32 s39, s9, 0
	s_add_u32 s8, s24, 0x100
	v_mov_b64_e32 v[0:1], 0
	s_addc_u32 s9, s25, 0
	s_mov_b32 s42, -2
	v_mov_b64_e32 v[2:3], 0
	v_mov_b64_e32 v[4:5], 0
	v_mov_b64_e32 v[6:7], 0
	v_mov_b64_e32 v[16:17], 0
	v_mov_b64_e32 v[18:19], 0
	v_mov_b64_e32 v[20:21], 0
	v_mov_b64_e32 v[22:23], 0
	v_mov_b64_e32 v[32:33], 0
	v_mov_b64_e32 v[34:35], 0
	v_mov_b64_e32 v[36:37], 0
	v_mov_b64_e32 v[38:39], 0
	v_mov_b64_e32 v[48:49], 0
	v_mov_b64_e32 v[50:51], 0
	v_mov_b64_e32 v[52:53], 0
	v_mov_b64_e32 v[54:55], 0
	v_mov_b64_e32 v[8:9], 0
	v_mov_b64_e32 v[10:11], 0
	v_mov_b64_e32 v[12:13], 0
	v_mov_b64_e32 v[14:15], 0
	v_mov_b64_e32 v[24:25], 0
	v_mov_b64_e32 v[26:27], 0
	v_mov_b64_e32 v[28:29], 0
	v_mov_b64_e32 v[30:31], 0
	v_mov_b64_e32 v[40:41], 0
	v_mov_b64_e32 v[42:43], 0
	v_mov_b64_e32 v[44:45], 0
	v_mov_b64_e32 v[46:47], 0
	v_mov_b64_e32 v[72:73], 0
	v_mov_b64_e32 v[74:75], 0
	v_mov_b64_e32 v[76:77], 0
	v_mov_b64_e32 v[78:79], 0
	v_mov_b64_e32 v[80:81], 0
	v_mov_b64_e32 v[82:83], 0
	v_mov_b64_e32 v[84:85], 0
	v_mov_b64_e32 v[86:87], 0
	v_mov_b64_e32 v[96:97], 0
	v_mov_b64_e32 v[98:99], 0
	v_mov_b64_e32 v[100:101], 0
	v_mov_b64_e32 v[102:103], 0
	v_mov_b64_e32 v[112:113], 0
	v_mov_b64_e32 v[114:115], 0
	v_mov_b64_e32 v[116:117], 0
	v_mov_b64_e32 v[118:119], 0
	v_mov_b64_e32 v[128:129], 0
	v_mov_b64_e32 v[130:131], 0
	v_mov_b64_e32 v[132:133], 0
	v_mov_b64_e32 v[134:135], 0
	v_mov_b64_e32 v[88:89], 0
	v_mov_b64_e32 v[90:91], 0
	v_mov_b64_e32 v[92:93], 0
	v_mov_b64_e32 v[94:95], 0
	v_mov_b64_e32 v[104:105], 0
	v_mov_b64_e32 v[106:107], 0
	v_mov_b64_e32 v[108:109], 0
	v_mov_b64_e32 v[110:111], 0
	v_mov_b64_e32 v[120:121], 0
	v_mov_b64_e32 v[122:123], 0
	v_mov_b64_e32 v[124:125], 0
	v_mov_b64_e32 v[126:127], 0
	v_mov_b64_e32 v[136:137], 0
	v_mov_b64_e32 v[138:139], 0
	v_mov_b64_e32 v[140:141], 0
	v_mov_b64_e32 v[142:143], 0
